# next-unit tile coordinates computed inside the peeled first K-tile (branch-free SALU, hidden behind the other half's MFMA block) instead of in the unit header, in-projection and gate|up GEMMs
# baseline (speedup 1.0000x reference)
.LBB0_309:
	v_lshlrev_b32_e32 v142, 4, v0
	s_lshl_b32 s100, s57, 14
	s_add_u32 s100, s18, s100
	s_addc_u32 s101, s19, 0
	v_readfirstlane_b32 s25, v142
	s_nop 3
	s_add_i32 m0, s25, 0x20400
	s_nop 0
	global_load_lds_dwordx4 v142, s[100:101]
	v_add_u32_e32 v142, 0x2000, v142
	s_add_i32 m0, s25, 0x22400
	s_nop 0
	global_load_lds_dwordx4 v142, s[100:101]
	s_add_u32 s28, s28, 0x40080
	s_addc_u32 s29, s29, 0
	s_add_u32 s60, s30, 0x100
	s_addc_u32 s61, s31, 0
	s_mov_b32 s62, -2
.Lk7_peel:
	s_add_u32 s30, s28, 0xfffc0080
	s_addc_u32 s31, s29, -1
	s_add_i32 s63, 0, 0x10000
	s_cmp_eq_u32 s62, 12
	s_cselect_b32 s35, s25, s31
	s_cselect_b32 s34, s58, s30
	v_add_u32_e32 v142, s63, v145
	s_cselect_b32 s31, s23, s61
	s_cselect_b32 s30, s59, s60
	s_add_i32 s66, 0, 0x14000
	ds_read_b128 v[148:151], v142
	ds_read_b128 v[152:155], v142 offset:1024
	ds_read_b128 v[156:159], v142 offset:2048
	ds_read_b128 v[160:163], v142 offset:3072
	v_add_u32_e32 v142, s66, v145
	ds_read_b128 v[164:167], v142
	ds_read_b128 v[168:171], v142 offset:1024
	ds_read_b128 v[172:175], v142 offset:2048
	ds_read_b128 v[176:179], v142 offset:3072
	v_lshl_add_u64 v[142:143], s[28:29], 0, v[138:139]
	s_add_i32 m0, s45, 0xc000
	ds_read_b128 v[180:183], v146
	ds_read_b128 v[184:187], v146 offset:1024
	ds_read_b128 v[188:191], v146 offset:2048
	ds_read_b128 v[192:195], v146 offset:3072
	ds_read_b128 v[206:209], v146 offset:4096
	ds_read_b128 v[210:213], v146 offset:5120
	ds_read_b128 v[214:217], v146 offset:6144
	ds_read_b128 v[218:221], v146 offset:7168
	global_load_lds_dwordx4 v[142:143], off
	v_lshl_add_u64 v[142:143], s[28:29], 0, v[140:141]
	s_add_i32 m0, s45, 0xe000
	s_nop 0
	global_load_lds_dwordx4 v[142:143], off
	s_waitcnt vmcnt(8)
	s_waitcnt lgkmcnt(0)
	s_barrier
	s_waitcnt lgkmcnt(0)
	v_mfma_f32_16x16x32_bf16 v[128:131], v[148:151], v[180:183], 0
	v_mfma_f32_16x16x32_bf16 v[120:123], v[156:159], v[180:183], 0
	v_mfma_f32_16x16x32_bf16 v[112:115], v[148:151], v[188:191], 0
	v_mfma_f32_16x16x32_bf16 v[104:107], v[156:159], v[188:191], 0
	v_mfma_f32_16x16x32_bf16 v[96:99], v[148:151], v[206:209], 0
	v_mfma_f32_16x16x32_bf16 v[88:91], v[156:159], v[206:209], 0
	v_mfma_f32_16x16x32_bf16 v[80:83], v[148:151], v[214:217], 0
	v_mfma_f32_16x16x32_bf16 v[72:75], v[156:159], v[214:217], 0
	v_mfma_f32_16x16x32_bf16 v[128:131], v[152:155], v[184:187], v[128:131]
	v_mfma_f32_16x16x32_bf16 v[120:123], v[160:163], v[184:187], v[120:123]
	v_mfma_f32_16x16x32_bf16 v[112:115], v[152:155], v[192:195], v[112:115]
	v_mfma_f32_16x16x32_bf16 v[104:107], v[160:163], v[192:195], v[104:107]
	v_mfma_f32_16x16x32_bf16 v[96:99], v[152:155], v[210:213], v[96:99]
	v_mfma_f32_16x16x32_bf16 v[88:91], v[160:163], v[210:213], v[88:91]
	v_mfma_f32_16x16x32_bf16 v[80:83], v[152:155], v[218:221], v[80:83]
	v_mfma_f32_16x16x32_bf16 v[72:75], v[160:163], v[218:221], v[72:75]
	v_mfma_f32_16x16x32_bf16 v[124:127], v[164:167], v[180:183], 0
	v_mfma_f32_16x16x32_bf16 v[116:119], v[172:175], v[180:183], 0
	v_mfma_f32_16x16x32_bf16 v[108:111], v[164:167], v[188:191], 0
	v_mfma_f32_16x16x32_bf16 v[100:103], v[172:175], v[188:191], 0
	v_mfma_f32_16x16x32_bf16 v[92:95], v[164:167], v[206:209], 0
	v_mfma_f32_16x16x32_bf16 v[84:87], v[172:175], v[206:209], 0
	v_mfma_f32_16x16x32_bf16 v[76:79], v[164:167], v[214:217], 0
	v_mfma_f32_16x16x32_bf16 v[68:71], v[172:175], v[214:217], 0
	v_mfma_f32_16x16x32_bf16 v[124:127], v[168:171], v[184:187], v[124:127]
	v_mfma_f32_16x16x32_bf16 v[116:119], v[176:179], v[184:187], v[116:119]
	v_mfma_f32_16x16x32_bf16 v[108:111], v[168:171], v[192:195], v[108:111]
	v_mfma_f32_16x16x32_bf16 v[100:103], v[176:179], v[192:195], v[100:103]
	v_mfma_f32_16x16x32_bf16 v[92:95], v[168:171], v[210:213], v[92:95]
	v_mfma_f32_16x16x32_bf16 v[84:87], v[176:179], v[210:213], v[84:87]
	v_mfma_f32_16x16x32_bf16 v[76:79], v[168:171], v[218:221], v[76:79]
	v_mfma_f32_16x16x32_bf16 v[68:71], v[176:179], v[218:221], v[68:71]
	s_barrier
	s_add_i32 s63, s63, s36
	v_lshl_add_u64 v[142:143], s[30:31], 0, v[2:3]
	s_mov_b32 m0, s63
	ds_read_b128 v[180:183], v146 offset:16384
	ds_read_b128 v[184:187], v146 offset:17408
	ds_read_b128 v[188:191], v146 offset:18432
	ds_read_b128 v[192:195], v146 offset:19456
	ds_read_b128 v[206:209], v146 offset:20480
	ds_read_b128 v[210:213], v146 offset:21504
	ds_read_b128 v[214:217], v146 offset:22528
	ds_read_b128 v[218:221], v146 offset:23552
	global_load_lds_dwordx4 v[142:143], off
	s_add_i32 m0, s63, 0x2000
	s_add_u32 s64, s30, 0x40000
	v_lshl_add_u64 v[236:237], s[30:31], 0, v[132:133]
	s_addc_u32 s65, s31, 0
	s_add_i32 s63, s66, s36
	global_load_lds_dwordx4 v[236:237], off
	v_lshl_add_u64 v[238:239], s[64:65], 0, v[2:3]
	s_mov_b32 m0, s63
	v_lshl_add_u64 v[240:241], s[34:35], 0, v[134:135]
	global_load_lds_dwordx4 v[238:239], off
	v_lshl_add_u64 v[238:239], s[64:65], 0, v[132:133]
	s_add_i32 m0, s63, 0x2000
	s_nop 0
	global_load_lds_dwordx4 v[238:239], off
	v_lshl_add_u64 v[238:239], s[34:35], 0, v[136:137]
	s_mov_b32 m0, s45
	s_nop 0
	global_load_lds_dwordx4 v[238:239], off
	s_mov_b32 m0, s46
	s_nop 0
	global_load_lds_dwordx4 v[240:241], off
	s_add_i32 s55, s55, 1
	s_mul_i32 s23, s55, s84
	s_mul_hi_u32 s25, s55, s83
	s_add_i32 s25, s25, s23
	s_mul_i32 s23, s55, s83
	s_add_u32 s100, s23, s2
	s_addc_u32 s101, s25, s93
	v_cmp_gt_i64_e32 vcc, s[100:101], v[202:203]
	v_cmp_lt_i64_e64 s[38:39], s[100:101], v[200:201]
	s_cbranch_vccnz .Lm7_nonext
	s_and_b32 s25, s100, 7
	s_lshr_b32 s23, s100, 3
	s_mul_i32 s101, s25, 0xb3
	s_sub_i32 s100, s25, 6
	s_max_i32 s100, s100, 0
	s_sub_i32 s101, s101, s100
	s_add_i32 s23, s23, s101
	s_mul_hi_i32 s25, s23, 0x2e8ba2e9
	s_ashr_i32 s25, s25, 3
	s_mul_i32 s101, s25, 44
	s_sub_i32 s23, s23, s101
	s_lshl_b32 s25, s25, 1
	s_sub_i32 s101, 0x41, s25
	s_min_i32 s101, s101, 2
	s_sub_i32 s101, s101, 1
	s_lshr_b32 s22, s23, s101
	s_and_b32 s23, s23, s101
	s_add_i32 s24, s25, s23
.Lm7_nonext:
	s_lshl_b32 s100, s24, 19
	s_add_u32 s26, s37, s100
	s_addc_u32 s27, s44, 0
	s_and_b64 s[100:101], s[38:39], exec
	s_cselect_b32 s25, s27, s29
	s_cselect_b32 s58, s26, s28
	s_lshl_b32 s100, s22, 19
	s_add_u32 s42, s40, s100
	s_addc_u32 s43, s41, 0
	s_and_b64 s[100:101], s[38:39], exec
	s_cselect_b32 s23, s43, s61
	s_cselect_b32 s59, s42, s60
	s_waitcnt vmcnt(8)
	s_waitcnt lgkmcnt(0)
	s_barrier
	s_waitcnt lgkmcnt(0)
	v_mfma_f32_16x16x32_bf16 v[64:67], v[148:151], v[180:183], 0
	v_mfma_f32_16x16x32_bf16 v[56:59], v[156:159], v[180:183], 0
	v_mfma_f32_16x16x32_bf16 v[48:51], v[148:151], v[188:191], 0
	v_mfma_f32_16x16x32_bf16 v[40:43], v[156:159], v[188:191], 0
	v_mfma_f32_16x16x32_bf16 v[32:35], v[148:151], v[206:209], 0
	v_mfma_f32_16x16x32_bf16 v[24:27], v[156:159], v[206:209], 0
	v_mfma_f32_16x16x32_bf16 v[16:19], v[148:151], v[214:217], 0
	v_mfma_f32_16x16x32_bf16 v[8:11], v[156:159], v[214:217], 0
	v_mfma_f32_16x16x32_bf16 v[64:67], v[152:155], v[184:187], v[64:67]
	v_mfma_f32_16x16x32_bf16 v[56:59], v[160:163], v[184:187], v[56:59]
	v_mfma_f32_16x16x32_bf16 v[48:51], v[152:155], v[192:195], v[48:51]
	v_mfma_f32_16x16x32_bf16 v[40:43], v[160:163], v[192:195], v[40:43]
	v_mfma_f32_16x16x32_bf16 v[32:35], v[152:155], v[210:213], v[32:35]
	v_mfma_f32_16x16x32_bf16 v[24:27], v[160:163], v[210:213], v[24:27]
	v_mfma_f32_16x16x32_bf16 v[16:19], v[152:155], v[218:221], v[16:19]
	v_mfma_f32_16x16x32_bf16 v[8:11], v[160:163], v[218:221], v[8:11]
	v_mfma_f32_16x16x32_bf16 v[60:63], v[164:167], v[180:183], 0
	v_mfma_f32_16x16x32_bf16 v[52:55], v[172:175], v[180:183], 0
	v_mfma_f32_16x16x32_bf16 v[44:47], v[164:167], v[188:191], 0
	v_mfma_f32_16x16x32_bf16 v[36:39], v[172:175], v[188:191], 0
	v_mfma_f32_16x16x32_bf16 v[28:31], v[164:167], v[206:209], 0
	v_mfma_f32_16x16x32_bf16 v[20:23], v[172:175], v[206:209], 0
	v_mfma_f32_16x16x32_bf16 v[12:15], v[164:167], v[214:217], 0
	v_mfma_f32_16x16x32_bf16 v[4:7], v[172:175], v[214:217], 0
	v_mfma_f32_16x16x32_bf16 v[60:63], v[168:171], v[184:187], v[60:63]
	v_mfma_f32_16x16x32_bf16 v[52:55], v[176:179], v[184:187], v[52:55]
	v_mfma_f32_16x16x32_bf16 v[44:47], v[168:171], v[192:195], v[44:47]
	v_mfma_f32_16x16x32_bf16 v[36:39], v[176:179], v[192:195], v[36:39]
	v_mfma_f32_16x16x32_bf16 v[28:31], v[168:171], v[210:213], v[28:31]
	v_mfma_f32_16x16x32_bf16 v[20:23], v[176:179], v[210:213], v[20:23]
	v_mfma_f32_16x16x32_bf16 v[12:15], v[168:171], v[218:221], v[12:15]
	v_mfma_f32_16x16x32_bf16 v[4:7], v[176:179], v[218:221], v[4:7]
	s_barrier
	s_add_i32 s63, 0, 0x18000
	v_add_u32_e32 v147, s63, v145
	s_add_i32 s64, 0, 0x1c000
	ds_read_b128 v[148:151], v147
	ds_read_b128 v[152:155], v147 offset:1024
	ds_read_b128 v[156:159], v147 offset:2048
	ds_read_b128 v[160:163], v147 offset:3072
	v_add_u32_e32 v147, s64, v145
	ds_read_b128 v[164:167], v147
	ds_read_b128 v[168:171], v147 offset:1024
	ds_read_b128 v[172:175], v147 offset:2048
	ds_read_b128 v[176:179], v147 offset:3072
	s_add_u32 s34, s34, 0x40000
	s_addc_u32 s35, s35, 0
	s_mov_b32 m0, s47
	v_lshl_add_u64 v[242:243], s[34:35], 0, v[136:137]
	ds_read_b128 v[180:183], v146 offset:32768
	ds_read_b128 v[184:187], v146 offset:33792
	ds_read_b128 v[188:191], v146 offset:34816
	ds_read_b128 v[192:195], v146 offset:35840
	ds_read_b128 v[206:209], v146 offset:36864
	ds_read_b128 v[210:213], v146 offset:37888
	ds_read_b128 v[214:217], v146 offset:38912
	ds_read_b128 v[218:221], v146 offset:39936
	global_load_lds_dwordx4 v[242:243], off
	v_lshl_add_u64 v[242:243], s[34:35], 0, v[134:135]
	s_mov_b32 m0, s48
	s_nop 0
	global_load_lds_dwordx4 v[242:243], off
	s_waitcnt vmcnt(8)
	s_waitcnt lgkmcnt(0)
	s_barrier
	s_waitcnt lgkmcnt(0)
	v_mfma_f32_16x16x32_bf16 v[128:131], v[148:151], v[180:183], v[128:131]
	v_mfma_f32_16x16x32_bf16 v[120:123], v[156:159], v[180:183], v[120:123]
	v_mfma_f32_16x16x32_bf16 v[112:115], v[148:151], v[188:191], v[112:115]
	v_mfma_f32_16x16x32_bf16 v[104:107], v[156:159], v[188:191], v[104:107]
	v_mfma_f32_16x16x32_bf16 v[96:99], v[148:151], v[206:209], v[96:99]
	v_mfma_f32_16x16x32_bf16 v[88:91], v[156:159], v[206:209], v[88:91]
	v_mfma_f32_16x16x32_bf16 v[80:83], v[148:151], v[214:217], v[80:83]
	v_mfma_f32_16x16x32_bf16 v[72:75], v[156:159], v[214:217], v[72:75]
	v_mfma_f32_16x16x32_bf16 v[128:131], v[152:155], v[184:187], v[128:131]
	v_mfma_f32_16x16x32_bf16 v[120:123], v[160:163], v[184:187], v[120:123]
	v_mfma_f32_16x16x32_bf16 v[112:115], v[152:155], v[192:195], v[112:115]
	v_mfma_f32_16x16x32_bf16 v[104:107], v[160:163], v[192:195], v[104:107]
	v_mfma_f32_16x16x32_bf16 v[96:99], v[152:155], v[210:213], v[96:99]
	v_mfma_f32_16x16x32_bf16 v[88:91], v[160:163], v[210:213], v[88:91]
	v_mfma_f32_16x16x32_bf16 v[80:83], v[152:155], v[218:221], v[80:83]
	v_mfma_f32_16x16x32_bf16 v[72:75], v[160:163], v[218:221], v[72:75]
	v_mfma_f32_16x16x32_bf16 v[124:127], v[164:167], v[180:183], v[124:127]
	v_mfma_f32_16x16x32_bf16 v[116:119], v[172:175], v[180:183], v[116:119]
	v_mfma_f32_16x16x32_bf16 v[108:111], v[164:167], v[188:191], v[108:111]
	v_mfma_f32_16x16x32_bf16 v[100:103], v[172:175], v[188:191], v[100:103]
	v_mfma_f32_16x16x32_bf16 v[92:95], v[164:167], v[206:209], v[92:95]
	v_mfma_f32_16x16x32_bf16 v[84:87], v[172:175], v[206:209], v[84:87]
	v_mfma_f32_16x16x32_bf16 v[76:79], v[164:167], v[214:217], v[76:79]
	v_mfma_f32_16x16x32_bf16 v[68:71], v[172:175], v[214:217], v[68:71]
	v_mfma_f32_16x16x32_bf16 v[124:127], v[168:171], v[184:187], v[124:127]
	v_mfma_f32_16x16x32_bf16 v[116:119], v[176:179], v[184:187], v[116:119]
	v_mfma_f32_16x16x32_bf16 v[108:111], v[168:171], v[192:195], v[108:111]
	v_mfma_f32_16x16x32_bf16 v[100:103], v[176:179], v[192:195], v[100:103]
	v_mfma_f32_16x16x32_bf16 v[92:95], v[168:171], v[210:213], v[92:95]
	v_mfma_f32_16x16x32_bf16 v[84:87], v[176:179], v[210:213], v[84:87]
	v_mfma_f32_16x16x32_bf16 v[76:79], v[168:171], v[218:221], v[76:79]
	v_mfma_f32_16x16x32_bf16 v[68:71], v[176:179], v[218:221], v[68:71]
	s_barrier
	s_add_i32 s34, s63, s36
	v_lshl_add_u64 v[142:143], v[142:143], 0, s[96:97]
	s_mov_b32 m0, s34
	ds_read_b128 v[180:183], v146 offset:49152
	ds_read_b128 v[184:187], v146 offset:50176
	ds_read_b128 v[188:191], v146 offset:51200
	ds_read_b128 v[192:195], v146 offset:52224
	ds_read_b128 v[206:209], v146 offset:53248
	ds_read_b128 v[210:213], v146 offset:54272
	ds_read_b128 v[214:217], v146 offset:55296
	ds_read_b128 v[218:221], v146 offset:56320
	global_load_lds_dwordx4 v[142:143], off
	s_add_i32 m0, s34, 0x2000
	s_add_u32 s30, s30, 0x40080
	v_lshl_add_u64 v[142:143], v[236:237], 0, s[96:97]
	s_addc_u32 s31, s31, 0
	s_add_i32 s34, s64, s36
	global_load_lds_dwordx4 v[142:143], off
	v_lshl_add_u64 v[142:143], s[30:31], 0, v[2:3]
	s_mov_b32 m0, s34
	s_nop 0
	global_load_lds_dwordx4 v[142:143], off
	v_lshl_add_u64 v[142:143], s[30:31], 0, v[132:133]
	s_add_i32 m0, s34, 0x2000
	s_nop 0
	global_load_lds_dwordx4 v[142:143], off
	v_lshl_add_u64 v[142:143], v[238:239], 0, s[96:97]
	s_mov_b32 m0, s51
	s_nop 0
	global_load_lds_dwordx4 v[142:143], off
	v_lshl_add_u64 v[142:143], v[240:241], 0, s[96:97]
	s_mov_b32 m0, s52
	s_nop 0
	global_load_lds_dwordx4 v[142:143], off
	s_waitcnt vmcnt(8)
	s_waitcnt lgkmcnt(0)
	s_barrier
	s_waitcnt lgkmcnt(0)
	v_mfma_f32_16x16x32_bf16 v[64:67], v[148:151], v[180:183], v[64:67]
	v_mfma_f32_16x16x32_bf16 v[56:59], v[156:159], v[180:183], v[56:59]
	v_mfma_f32_16x16x32_bf16 v[48:51], v[148:151], v[188:191], v[48:51]
	v_mfma_f32_16x16x32_bf16 v[40:43], v[156:159], v[188:191], v[40:43]
	v_mfma_f32_16x16x32_bf16 v[32:35], v[148:151], v[206:209], v[32:35]
	v_mfma_f32_16x16x32_bf16 v[24:27], v[156:159], v[206:209], v[24:27]
	v_mfma_f32_16x16x32_bf16 v[16:19], v[148:151], v[214:217], v[16:19]
	v_mfma_f32_16x16x32_bf16 v[8:11], v[156:159], v[214:217], v[8:11]
	v_mfma_f32_16x16x32_bf16 v[64:67], v[152:155], v[184:187], v[64:67]
	v_mfma_f32_16x16x32_bf16 v[56:59], v[160:163], v[184:187], v[56:59]
	v_mfma_f32_16x16x32_bf16 v[48:51], v[152:155], v[192:195], v[48:51]
	v_mfma_f32_16x16x32_bf16 v[40:43], v[160:163], v[192:195], v[40:43]
	v_mfma_f32_16x16x32_bf16 v[32:35], v[152:155], v[210:213], v[32:35]
	v_mfma_f32_16x16x32_bf16 v[24:27], v[160:163], v[210:213], v[24:27]
	v_mfma_f32_16x16x32_bf16 v[16:19], v[152:155], v[218:221], v[16:19]
	v_mfma_f32_16x16x32_bf16 v[8:11], v[160:163], v[218:221], v[8:11]
	v_mfma_f32_16x16x32_bf16 v[60:63], v[164:167], v[180:183], v[60:63]
	v_mfma_f32_16x16x32_bf16 v[52:55], v[172:175], v[180:183], v[52:55]
	v_mfma_f32_16x16x32_bf16 v[44:47], v[164:167], v[188:191], v[44:47]
	v_mfma_f32_16x16x32_bf16 v[36:39], v[172:175], v[188:191], v[36:39]
	v_mfma_f32_16x16x32_bf16 v[28:31], v[164:167], v[206:209], v[28:31]
	v_mfma_f32_16x16x32_bf16 v[20:23], v[172:175], v[206:209], v[20:23]
	v_mfma_f32_16x16x32_bf16 v[12:15], v[164:167], v[214:217], v[12:15]
	v_mfma_f32_16x16x32_bf16 v[4:7], v[172:175], v[214:217], v[4:7]
	v_mfma_f32_16x16x32_bf16 v[60:63], v[168:171], v[184:187], v[60:63]
	v_mfma_f32_16x16x32_bf16 v[52:55], v[176:179], v[184:187], v[52:55]
	v_mfma_f32_16x16x32_bf16 v[44:47], v[168:171], v[192:195], v[44:47]
	v_mfma_f32_16x16x32_bf16 v[36:39], v[176:179], v[192:195], v[36:39]
	v_mfma_f32_16x16x32_bf16 v[28:31], v[168:171], v[210:213], v[28:31]
	v_mfma_f32_16x16x32_bf16 v[20:23], v[176:179], v[210:213], v[20:23]
	v_mfma_f32_16x16x32_bf16 v[12:15], v[168:171], v[218:221], v[12:15]
	v_mfma_f32_16x16x32_bf16 v[4:7], v[176:179], v[218:221], v[4:7]
	s_barrier
	s_add_i32 s62, s62, 2
	s_add_u32 s28, s28, 0x100
	s_addc_u32 s29, s29, 0
	s_add_u32 s60, s60, 0x100
	s_addc_u32 s61, s61, 0
	s_cmp_gt_u32 s62, 13

.LBB0_745:
	v_lshlrev_b32_e32 v2, 4, v0
	s_lshl_b32 s22, s16, 14
	s_add_u32 s22, s50, s22
	s_addc_u32 s23, s51, 0
	v_readfirstlane_b32 s57, v2
	s_nop 3
	s_add_i32 m0, s57, 0x20400
	s_nop 0
	global_load_lds_dwordx4 v2, s[22:23]
	v_add_u32_e32 v2, 0x2000, v2
	s_add_i32 m0, s57, 0x22400
	s_nop 0
	global_load_lds_dwordx4 v2, s[22:23]
	s_add_u32 s18, s18, 0x40080
	s_addc_u32 s19, s19, 0
	s_add_u32 s26, s20, 0x100
	s_addc_u32 s27, s21, 0
	s_mov_b32 s40, -2
	s_waitcnt lgkmcnt(0)

.Lk1_wjb:
	s_waitcnt lgkmcnt(0)
	s_barrier
	s_waitcnt lgkmcnt(0)
	v_mfma_f32_16x16x32_bf16 v[120:123], v[144:147], v[180:183], 0
	v_mfma_f32_16x16x32_bf16 v[116:119], v[152:155], v[180:183], 0
	v_mfma_f32_16x16x32_bf16 v[104:107], v[144:147], v[188:191], 0
	v_mfma_f32_16x16x32_bf16 v[100:103], v[152:155], v[188:191], 0
	v_mfma_f32_16x16x32_bf16 v[88:91], v[144:147], v[206:209], 0
	v_mfma_f32_16x16x32_bf16 v[84:87], v[152:155], v[206:209], 0
	v_mfma_f32_16x16x32_bf16 v[72:75], v[144:147], v[214:217], 0
	v_mfma_f32_16x16x32_bf16 v[68:71], v[152:155], v[214:217], 0
	v_mfma_f32_16x16x32_bf16 v[120:123], v[148:151], v[184:187], v[120:123]
	v_mfma_f32_16x16x32_bf16 v[116:119], v[160:163], v[184:187], v[116:119]
	v_mfma_f32_16x16x32_bf16 v[104:107], v[148:151], v[192:195], v[104:107]
	v_mfma_f32_16x16x32_bf16 v[100:103], v[160:163], v[192:195], v[100:103]
	v_mfma_f32_16x16x32_bf16 v[88:91], v[148:151], v[210:213], v[88:91]
	v_mfma_f32_16x16x32_bf16 v[84:87], v[160:163], v[210:213], v[84:87]
	v_mfma_f32_16x16x32_bf16 v[72:75], v[148:151], v[218:221], v[72:75]
	v_mfma_f32_16x16x32_bf16 v[68:71], v[160:163], v[218:221], v[68:71]
	v_mfma_f32_16x16x32_bf16 v[128:131], v[164:167], v[180:183], 0
	v_mfma_f32_16x16x32_bf16 v[124:127], v[172:175], v[180:183], 0
	v_mfma_f32_16x16x32_bf16 v[112:115], v[164:167], v[188:191], 0
	v_mfma_f32_16x16x32_bf16 v[108:111], v[172:175], v[188:191], 0
	v_mfma_f32_16x16x32_bf16 v[96:99], v[164:167], v[206:209], 0
	v_mfma_f32_16x16x32_bf16 v[92:95], v[172:175], v[206:209], 0
	v_mfma_f32_16x16x32_bf16 v[80:83], v[164:167], v[214:217], 0
	v_mfma_f32_16x16x32_bf16 v[76:79], v[172:175], v[214:217], 0
	v_mfma_f32_16x16x32_bf16 v[128:131], v[168:171], v[184:187], v[128:131]
	v_mfma_f32_16x16x32_bf16 v[124:127], v[176:179], v[184:187], v[124:127]
	v_mfma_f32_16x16x32_bf16 v[112:115], v[168:171], v[192:195], v[112:115]
	v_mfma_f32_16x16x32_bf16 v[108:111], v[176:179], v[192:195], v[108:111]
	v_mfma_f32_16x16x32_bf16 v[96:99], v[168:171], v[210:213], v[96:99]
	v_mfma_f32_16x16x32_bf16 v[92:95], v[176:179], v[210:213], v[92:95]
	v_mfma_f32_16x16x32_bf16 v[80:83], v[168:171], v[218:221], v[80:83]
	v_mfma_f32_16x16x32_bf16 v[76:79], v[176:179], v[218:221], v[76:79]
	s_barrier
	s_add_i32 s41, s41, s35
	v_lshl_add_u64 v[234:235], s[20:21], 0, v[134:135]
	s_mov_b32 m0, s41
	ds_read_b128 v[180:183], v158 offset:16384
	ds_read_b128 v[184:187], v158 offset:17408
	ds_read_b128 v[188:191], v158 offset:18432
	ds_read_b128 v[192:195], v158 offset:19456
	ds_read_b128 v[206:209], v158 offset:20480
	ds_read_b128 v[210:213], v158 offset:21504
	ds_read_b128 v[214:217], v158 offset:22528
	ds_read_b128 v[218:221], v158 offset:23552
	global_load_lds_dwordx4 v[234:235], off
	s_add_i32 m0, s41, 0x2000
	s_add_u32 s42, s20, 0x40000
	v_lshl_add_u64 v[236:237], s[20:21], 0, v[138:139]
	s_addc_u32 s43, s21, 0
	s_add_i32 s41, s55, s35
	global_load_lds_dwordx4 v[236:237], off
	v_lshl_add_u64 v[238:239], s[42:43], 0, v[134:135]
	s_mov_b32 m0, s41
	v_lshl_add_u64 v[240:241], s[22:23], 0, v[136:137]
	global_load_lds_dwordx4 v[238:239], off
	v_lshl_add_u64 v[238:239], s[42:43], 0, v[138:139]
	s_add_i32 m0, s41, 0x2000
	s_nop 0
	global_load_lds_dwordx4 v[238:239], off
	v_lshl_add_u64 v[238:239], s[22:23], 0, v[132:133]
	s_mov_b32 m0, s36
	s_nop 0
	global_load_lds_dwordx4 v[238:239], off
	s_mov_b32 m0, s37
	s_nop 0
	global_load_lds_dwordx4 v[240:241], off
	s_add_i32 s72, s72, 1
	s_mul_i32 s15, s72, s84
	s_mul_hi_u32 s17, s72, s83
	s_add_i32 s17, s17, s15
	s_mul_i32 s15, s72, s83
	s_add_u32 s62, s15, s2
	s_addc_u32 s63, s17, s93
	v_cmp_gt_i64_e32 vcc, s[62:63], v[202:203]
	v_cmp_lt_i64_e64 s[38:39], s[62:63], v[200:201]
	s_cbranch_vccnz .Lm1_nonext
	s_and_b32 s17, s62, 7
	s_lshr_b32 s15, s62, 3
	s_mul_i32 s63, s17, 0xb3
	s_sub_i32 s101, s17, 6
	s_max_i32 s101, s101, 0
	s_sub_i32 s63, s63, s101
	s_add_i32 s15, s15, s63
	s_mul_hi_i32 s17, s15, 0x2e8ba2e9
	s_ashr_i32 s17, s17, 3
	s_mul_i32 s63, s17, 44
	s_sub_i32 s15, s15, s63
	s_lshl_b32 s17, s17, 1
	s_sub_i32 s63, 0x41, s17
	s_min_i32 s63, s63, 2
	s_sub_i32 s63, s63, 1
	s_lshr_b32 s54, s15, s63
	s_and_b32 s15, s15, s63
	s_add_i32 s56, s17, s15
.Lm1_nonext:
	s_lshl_b32 s62, s56, 19
	s_add_u32 s58, s28, s62
	s_addc_u32 s59, s29, 0
	s_and_b64 s[62:63], s[38:39], exec
	s_cselect_b32 s15, s59, s19
	s_cselect_b32 s17, s58, s18
	s_lshl_b32 s62, s54, 19
	s_add_u32 s60, s30, s62
	s_addc_u32 s61, s31, 0
	s_and_b64 s[62:63], s[38:39], exec
	s_cselect_b32 s24, s61, s27
	s_cselect_b32 s25, s60, s26
	s_cmp_eq_u32 s100, 1
	s_cbranch_scc1 .Lk1_w26a
	s_waitcnt vmcnt(10)
	s_branch .Lk1_wja
